# GE1: GEMM1 phase entry: first unit's 8 LDS-DMA tile requests issued before the row-scale preparation instead of after it
# speedup vs baseline: 1.0006x; 1.0006x over previous
; #define LAS __attribute__((address_space(3)))
;     __device__ bool next(int i, Unit& u) const { const long L = (long)i * G + c; if (L >= hi) return false; unit_of((int)L, u); return true; }
; #define PG8_STAGE(bufoff, gbase) do { _Pragma("unroll") for (int _i = 0; _i < 2; ++_i) \
;         __builtin_amdgcn_global_load_lds((const unsigned*)((const char*)(gbase) + voffA[_i]), (LAS unsigned*)(lds + (bufoff) + ldsw + _i * 8192), 16, 0, 0); } while (0)
; template <class Epi, bool SPLITA>
; __device__ __forceinline__ void gemm_phase(LAS unsigned char* lds, const Gemm g, const StaticOrder& S, const Epi& E) {
;     ...
;     const char* cB = (const char*)g.Bt + (size_t)cur.pn * tstep;
;     PG8_STAGE(PG8_SB(0, 0), cB); PG8_STAGE(PG8_SB(0, 1), cB + hstep); PG8_STAGE_A(PG8_SA(0, 0), cur.pm, 0, 0); PG8_STAGE_A(PG8_SA(0, 1), cur.pm, 0, 1);
;     __device__ __forceinline__ void prepare(LAS unsigned char* lds, const pg8::StaticOrder& S, int tid) const {
;         const float* SS = (const float*)(ws + WS_SS);
;         f32x4 p0[9], p1[9];
; #pragma unroll
;         for (int i = 0; i < 9; ++i) {
;             pg8::Unit u; p0[i] = (f32x4){0.f, 0.f, 0.f, 0.f}; p1[i] = p0[i];
;             if (S.next(i, u)) { const float* sp = SS + (size_t)(u.pm * 256 + (tid >> 1)) * 16 + (tid & 1) * 8; p0[i] = *(const f32x4*)sp; p1[i] = *(const f32x4*)(sp + 4); }
;         }
.LBB0_166:
	s_andn2_b64 vcc, exec, s[0:1]
	s_cbranch_vccnz .LBB0_384
	v_readlane_b32 s0, v254, 51
	s_load_dword s94, s[86:87], 0x0
	v_readlane_b32 s1, v254, 52
	s_mov_b32 s5, s1
	s_mul_i32 s4, s99, 0x2c0000
	s_lshl_b64 s[0:1], s[4:5], 1
	v_readlane_b32 s4, v254, 2
	s_add_u32 s96, s4, s0
	v_readlane_b32 s0, v254, 3
	s_addc_u32 s97, s0, s1
	s_waitcnt lgkmcnt(0)
	s_cmpk_eq_i32 s94, 0x100
	s_cselect_b64 s[6:7], -1, 0
	s_and_b64 s[0:1], s[6:7], exec
	s_movk_i32 s0, 0x800
	s_cselect_b32 s98, s0, 0x840
	s_lshl_b32 s4, s99, 6
	v_writelane_b32 v254, s4, 51
	v_mov_b32_e32 v76, v0
	s_cmp_ge_i32 s2, s98
	v_writelane_b32 v254, s5, 52
	v_readfirstlane_b32 s10, v76
	s_cbranch_scc1 .LBB0_317
	s_waitcnt vmcnt(0)
	s_mov_b64 s[100:101], s[6:7]
	v_readlane_b32 s70, v254, 25
	v_readlane_b32 s52, v254, 27
	s_nop 3
	v_ashrrev_i32_e32 v3, 31, v76
	v_lshrrev_b32_e32 v3, 26, v3
	v_add_u32_e32 v3, v76, v3
	v_ashrrev_i32_e32 v10, 6, v3
	v_bfe_i32 v3, v76, 27, 1
	v_lshlrev_b32_e32 v2, 4, v76
	v_lshrrev_b32_e32 v3, 22, v3
	v_add_u32_e32 v3, v2, v3
	v_and_b32_e32 v3, 0xfffffc00, v3
	v_sub_u32_e32 v3, v2, v3
	v_lshrrev_b32_e32 v4, 4, v3
	v_bitop3_b32 v3, v4, v3, 32 bitop3:0x6c
	v_ashrrev_i32_e32 v5, 31, v3
	v_lshrrev_b32_e32 v5, 26, v5
	v_add_u32_e32 v5, v3, v5
	v_ashrrev_i32_e32 v11, 6, v5
	v_and_b32_e32 v5, 0xc0, v5
	v_sub_u32_e32 v3, v3, v5
	v_lshlrev_b32_e32 v4, 3, v10
	v_lshlrev_b32_e32 v6, 5, v10
	v_ashrrev_i16_sdwa v3, v224, sext(v3) dst_sel:DWORD dst_unused:UNUSED_PAD src0_sel:DWORD src1_sel:BYTE_0
	v_and_b32_e32 v4, 0x1ffff0, v4
	v_and_b32_e32 v6, 32, v6
	v_bfe_i32 v13, v3, 0, 16
	v_add_u32_e32 v3, v6, v13
	v_add_lshl_u32 v4, v11, v4, 11
	v_add_u32_e32 v2, 0x2000, v2
	v_lshl_add_u32 v154, v3, 1, v4
	v_ashrrev_i32_e32 v3, 31, v2
	v_lshrrev_b32_e32 v3, 22, v3
	v_add_u32_e32 v3, v2, v3
	v_ashrrev_i32_e32 v12, 10, v3
	v_mul_i32_i24_e32 v3, 0x400, v12
	v_sub_u32_e32 v2, v2, v3
	v_lshrrev_b32_e32 v3, 4, v2
	v_bitop3_b32 v2, v3, v2, 32 bitop3:0x6c
	v_ashrrev_i32_e32 v4, 31, v2
	v_lshrrev_b32_e32 v4, 26, v4
	s_ashr_i32 s4, s10, 6
	v_add_u32_e32 v4, v2, v4
	s_ashr_i32 s53, s52, 31
	v_ashrrev_i32_e32 v14, 6, v4
	v_and_b32_e32 v4, 0xc0, v4
	s_ashr_i32 s5, s10, 8
	s_lshl_b32 s95, s4, 10
	s_lshl_b64 s[0:1], s[52:53], 19
	v_sub_u32_e32 v2, v2, v4
	s_add_u32 s0, s96, s0
	v_lshlrev_b32_e32 v3, 3, v12
	v_lshlrev_b32_e32 v5, 5, v12
	v_ashrrev_i16_sdwa v2, v224, sext(v2) dst_sel:DWORD dst_unused:UNUSED_PAD src0_sel:DWORD src1_sel:BYTE_0
	s_addc_u32 s1, s97, s1
	s_add_i32 s8, s95, 0
	v_and_b32_e32 v3, 0x1ffff0, v3
	v_and_b32_e32 v5, 32, v5
	v_bfe_i32 v15, v2, 0, 16
	s_add_i32 m0, s8, 0x10000
	v_add_u32_e32 v2, v5, v15
	v_add_lshl_u32 v3, v14, v3, 11
	global_load_lds_dwordx4 v154, s[0:1]
	s_add_i32 m0, s8, 0x12000
	v_lshl_add_u32 v156, v2, 1, v3
	s_add_u32 s6, s0, 0x40000
	global_load_lds_dwordx4 v156, s[0:1]
	s_addc_u32 s7, s1, 0
	s_add_i32 m0, s8, 0x14000
	s_ashr_i32 s71, s70, 31
	global_load_lds_dwordx4 v154, s[6:7]
	s_add_i32 m0, s8, 0x16000
	v_mov_b32_e32 v155, v195
	global_load_lds_dwordx4 v156, s[6:7]
	s_lshl_b64 s[6:7], s[70:71], 19
	s_add_u32 s6, s40, s6
	s_addc_u32 s7, s41, s7
	s_add_i32 s9, s8, 0x2000
	s_mov_b32 m0, s8
	s_add_u32 s12, s6, 0x40000
	global_load_lds_dwordx4 v154, s[6:7]
	s_mov_b32 m0, s9
	s_addc_u32 s13, s7, 0
	s_add_i32 s37, s8, 0x4000
	global_load_lds_dwordx4 v156, s[6:7]
	s_mov_b32 m0, s37
	s_add_i32 s31, s8, 0x6000
	global_load_lds_dwordx4 v154, s[12:13]
	s_mov_b32 m0, s31
	s_cmp_eq_u32 s5, 1
	global_load_lds_dwordx4 v156, s[12:13]
	s_mov_b64 s[6:7], s[100:101]
	v_lshlrev_b32_e32 v2, 5, v76
	v_readlane_b32 s0, v254, 4
	v_and_b32_e32 v194, 32, v2
	v_readlane_b32 s1, v254, 5
	v_ashrrev_i32_e32 v77, 1, v76
	v_writelane_b32 v255, s6, 2
	v_lshl_add_u64 v[74:75], s[0:1], 0, v[194:195]
	v_readlane_b32 s0, v254, 29
	v_writelane_b32 v255, s7, 3
	s_ashr_i32 s4, s94, 31
	v_add_u32_e32 v2, s0, v77
	v_ashrrev_i32_e32 v3, 31, v2
	v_lshlrev_b64 v[2:3], 6, v[2:3]
	v_lshl_add_u64 v[2:3], v[74:75], 0, v[2:3]
	global_load_dwordx4 v[6:9], v[2:3], off offset:16
	global_load_dwordx4 v[10:13], v[2:3], off
	v_readlane_b32 s0, v254, 51
	v_readlane_b32 s1, v254, 52
	v_writelane_b32 v255, s99, 4
	s_mov_b32 s99, s1
	s_add_u32 s0, s94, s2
	s_addc_u32 s1, s4, s3
	v_mov_b64_e32 v[2:3], s[98:99]
	v_cmp_ge_i64_e32 vcc, s[0:1], v[2:3]
	v_mov_b32_e32 v2, 0
	s_and_b64 vcc, exec, vcc
	v_mov_b32_e32 v14, 0
	v_mov_b32_e32 v15, 0
	v_mov_b32_e32 v16, 0
	v_mov_b32_e32 v17, 0
	v_mov_b32_e32 v18, 0
	v_mov_b32_e32 v19, 0
	v_mov_b32_e32 v20, 0
	v_mov_b32_e32 v21, 0
	s_cbranch_vccnz .LBB0_170
	s_ashr_i32 s5, s0, 31
	s_lshr_b32 s5, s5, 29
	s_add_i32 s5, s0, s5
	s_ashr_i32 s6, s5, 3
	s_and_b32 s5, s5, -8
	s_sub_i32 s5, s0, s5
	s_cmp_lt_i32 s5, 0
	s_movk_i32 s7, 0x109
	s_cselect_b32 s7, s7, 0x108
	s_mul_i32 s5, s5, s7
	s_add_i32 s5, s5, s6
	s_mul_hi_i32 s6, s5, 0x2e8ba2e9
	s_lshr_b32 s7, s6, 31
	s_ashr_i32 s6, s6, 3
	s_add_i32 s6, s6, s7
	s_lshl_b32 s7, s6, 2
	s_sub_i32 s8, 0xc0, s7
	s_min_i32 s8, s8, 4
	s_abs_i32 s8, s8
	v_cvt_f32_u32_e32 v3, s8
	s_sub_i32 s9, 0, s8
	s_mul_i32 s6, s6, 44
	s_sub_i32 s5, s5, s6
	v_rcp_iflag_f32_e32 v3, v3
	s_ashr_i32 s6, s5, 31
	s_abs_i32 s5, s5
	v_mul_f32_e32 v3, 0x4f7ffffe, v3
	v_cvt_u32_f32_e32 v3, v3
	s_nop 0
	v_readfirstlane_b32 s11, v3
	s_mul_i32 s9, s9, s11
	s_mul_hi_u32 s9, s11, s9
	s_add_i32 s11, s11, s9
	s_mul_hi_u32 s9, s5, s11
	s_mul_i32 s9, s9, s8
	s_sub_i32 s5, s5, s9
	s_sub_i32 s9, s5, s8
	s_cmp_ge_u32 s5, s8
	s_cselect_b32 s5, s9, s5
	s_sub_i32 s9, s5, s8
	s_cmp_ge_u32 s5, s8
	s_cselect_b32 s5, s9, s5
	s_xor_b32 s5, s5, s6
	s_sub_i32 s5, s5, s6
	s_add_i32 s7, s7, s5
	v_lshl_add_u32 v4, s7, 8, v77
	v_ashrrev_i32_e32 v5, 31, v4
	v_lshlrev_b64 v[4:5], 6, v[4:5]
	v_lshl_add_u64 v[4:5], v[74:75], 0, v[4:5]
	global_load_dwordx4 v[14:17], v[4:5], off
	global_load_dwordx4 v[18:21], v[4:5], off offset:16

; #define PG8_STAGE(bufoff, gbase) do { _Pragma("unroll") for (int _i = 0; _i < 2; ++_i) \
;         __builtin_amdgcn_global_load_lds((const unsigned*)((const char*)(gbase) + voffA[_i]), (LAS unsigned*)(lds + (bufoff) + ldsw + _i * 8192), 16, 0, 0); } while (0)
; #define PG8_BAR __builtin_amdgcn_s_barrier()
; template <class Epi, bool SPLITA>
; __device__ __forceinline__ void gemm_phase(LAS unsigned char* lds, const Gemm g, const StaticOrder& S, const Epi& E) {
;     ...
;     for (int i = 0; i < 2; ++i) { int R, C; stage_rc(tid * 16 + i * 8192, R, C); voffA[i] = (unsigned)(R * K + C) * 2u; voffF[i] = (unsigned)((C >> 3) * 65536 + R * 16); voffM[i] = (unsigned)(R * 512 + C) * 2u; }
;     const size_t kstep = (size_t)(BK * 2);
;     const size_t hstep = (size_t)HALF * K * 2;
;     const size_t tstep = 2 * hstep;
;     const unsigned ldsw = (unsigned)wid * 1024u;
;     const int aoff = lds_byte(wr * 64 + fr, fq * 8), boff = lds_byte(wc * 32 + fr, fq * 8);
;     ...
;     PG8_STAGE(PG8_SB(0, 0), cB); PG8_STAGE(PG8_SB(0, 1), cB + hstep); PG8_STAGE_A(PG8_SA(0, 0), cur.pm, 0, 0); PG8_STAGE_A(PG8_SA(0, 1), cur.pm, 0, 1);
;     if (wr == 1) PG8_BAR;
.LBB0_202:
	v_writelane_b32 v255, s80, 6
	s_or_b64 exec, exec, s[4:5]
	s_waitcnt lgkmcnt(0)
	v_ashrrev_i32_e32 v3, 31, v76
	v_lshrrev_b32_e32 v3, 26, v3
	v_add_u32_e32 v3, v76, v3
	v_ashrrev_i32_e32 v10, 6, v3
	v_bfe_i32 v3, v76, 27, 1
	v_lshlrev_b32_e32 v2, 4, v76
	v_lshrrev_b32_e32 v3, 22, v3
	v_add_u32_e32 v3, v2, v3
	v_and_b32_e32 v3, 0xfffffc00, v3
	v_sub_u32_e32 v3, v2, v3
	v_lshrrev_b32_e32 v4, 4, v3
	v_bitop3_b32 v3, v4, v3, 32 bitop3:0x6c
	v_ashrrev_i32_e32 v5, 31, v3
	v_lshrrev_b32_e32 v5, 26, v5
	v_add_u32_e32 v5, v3, v5
	v_ashrrev_i32_e32 v11, 6, v5
	v_and_b32_e32 v5, 0xc0, v5
	v_sub_u32_e32 v3, v3, v5
	v_lshlrev_b32_e32 v4, 3, v10
	v_lshlrev_b32_e32 v6, 5, v10
	v_ashrrev_i16_sdwa v3, v224, sext(v3) dst_sel:DWORD dst_unused:UNUSED_PAD src0_sel:DWORD src1_sel:BYTE_0
	v_and_b32_e32 v4, 0x1ffff0, v4
	v_and_b32_e32 v6, 32, v6
	v_bfe_i32 v13, v3, 0, 16
	v_add_u32_e32 v3, v6, v13
	v_add_lshl_u32 v4, v11, v4, 11
	v_add_u32_e32 v2, 0x2000, v2
	v_lshl_add_u32 v154, v3, 1, v4
	v_ashrrev_i32_e32 v3, 31, v2
	v_lshrrev_b32_e32 v3, 22, v3
	v_add_u32_e32 v3, v2, v3
	v_ashrrev_i32_e32 v12, 10, v3
	v_mul_i32_i24_e32 v3, 0x400, v12
	v_sub_u32_e32 v2, v2, v3
	v_lshrrev_b32_e32 v3, 4, v2
	v_bitop3_b32 v2, v3, v2, 32 bitop3:0x6c
	v_ashrrev_i32_e32 v4, 31, v2
	v_lshrrev_b32_e32 v4, 26, v4
	s_ashr_i32 s4, s10, 6
	v_add_u32_e32 v4, v2, v4
	s_ashr_i32 s53, s52, 31
	v_ashrrev_i32_e32 v14, 6, v4
	v_and_b32_e32 v4, 0xc0, v4
	s_ashr_i32 s5, s10, 8
	s_lshl_b32 s95, s4, 10
	s_lshl_b64 s[0:1], s[52:53], 19
	v_sub_u32_e32 v2, v2, v4
	s_add_u32 s0, s96, s0
	v_lshlrev_b32_e32 v3, 3, v12
	v_lshlrev_b32_e32 v5, 5, v12
	v_ashrrev_i16_sdwa v2, v224, sext(v2) dst_sel:DWORD dst_unused:UNUSED_PAD src0_sel:DWORD src1_sel:BYTE_0
	s_addc_u32 s1, s97, s1
	s_add_i32 s8, s95, 0
	v_and_b32_e32 v3, 0x1ffff0, v3
	v_and_b32_e32 v5, 32, v5
	v_bfe_i32 v15, v2, 0, 16
	s_add_i32 m0, s8, 0x10000
	v_add_u32_e32 v2, v5, v15
	v_add_lshl_u32 v3, v14, v3, 11
	s_barrier
	s_add_i32 m0, s8, 0x12000
	v_lshl_add_u32 v156, v2, 1, v3
	s_add_u32 s6, s0, 0x40000
	s_addc_u32 s7, s1, 0
	s_add_i32 m0, s8, 0x14000
	s_ashr_i32 s71, s70, 31
	s_add_i32 m0, s8, 0x16000
	v_mov_b32_e32 v155, v195
	s_lshl_b64 s[6:7], s[70:71], 19
	s_add_u32 s6, s40, s6
	s_addc_u32 s7, s41, s7
	s_add_i32 s9, s8, 0x2000
	s_mov_b32 m0, s8
	s_add_u32 s12, s6, 0x40000
	s_mov_b32 m0, s9
	s_addc_u32 s13, s7, 0
	s_add_i32 s37, s8, 0x4000
	s_mov_b32 m0, s37
	s_add_i32 s31, s8, 0x6000
	s_mov_b32 m0, s31
	s_cmp_eq_u32 s5, 1
	s_cselect_b64 s[12:13], -1, 0
	v_mov_b32_e32 v157, v195
	v_writelane_b32 v255, s12, 8
	v_lshl_add_u64 v[8:9], s[0:1], 0, v[154:155]
	v_lshl_add_u64 v[6:7], s[0:1], 0, v[156:157]
	v_lshl_add_u64 v[2:3], s[6:7], 0, v[154:155]
	v_writelane_b32 v255, s13, 9
	s_cmp_lg_u32 s5, 1
	v_lshl_add_u64 v[4:5], s[6:7], 0, v[156:157]
	s_cbranch_scc1 .LBB0_204
	s_barrier
